# DSA v5: wave-private mask build (one barrier per chunk), SEL loads issued first, LDS-transposed epilogue with 16-byte stores
# baseline (speedup 1.0000x reference)
; #define LAS __attribute__((address_space(3)))
; #define LDS_WAIT() asm volatile("s_waitcnt lgkmcnt(0)" ::: "memory")
; __device__ __forceinline__ void dsa_unit(const bf16* QB, const int* SEL, bf16* AO, int b, int kvh, int t, LAS unsigned char* wl, int lane) {
;     const size_t rowbase = (size_t)b * SEQ, row = rowbase + t;
;     const int n = lane & 31, hi = lane >> 5, l15 = lane & 15, kq = lane >> 4;
;     const int ce = ((t >> 6) + 1) << 6; const int nsel = ce < 256 ? ce : 256;
;     LAS unsigned char* buf = wl;
;     LAS bf16* pT = (LAS bf16*)(wl + 9216);
;     LAS int* il = (LAS int*)(wl + 11264);
;     const LAS float* bl = (const LAS float*)(wl + 12288) + kvh * 128;
; __global__ void __launch_bounds__(NWAVES * 64, 2) fwd_megakernel(Args args) {
;     ...
;                 { LAS float* blw = (LAS float*)(wl + 12288);
; #pragma unroll
;                   for (int i = 0; i < 8; ++i) blw[lane + 64 * i] = LOG2E * args.in[I_RELB][lane + 64 * i];
;                   LDS_WAIT(); }
.Ldsa_new:
	v_readfirstlane_b32 s0, v207
	v_readlane_b32 s1, v251, 14
	v_readlane_b32 s12, v251, 0
	v_readlane_b32 s13, v251, 1
	s_lshr_b32 s0, s0, 6
	s_lshr_b32 s2, s84, 3
	s_mov_b32 s16, 0x88000
	s_mov_b32 s17, 0
	s_movk_i32 s23, 0x2200
	v_lshlrev_b32_e32 v178, 2, v207
	s_nop 4
	global_load_dword v179, v178, s[12:13]
	v_and_b32_e32 v64, 31, v206
	v_lshrrev_b32_e32 v65, 5, v206
	v_lshlrev_b32_e32 v175, 3, v65
	v_and_b32_e32 v66, 19, v64
	v_lshrrev_b32_e32 v67, 1, v64
	v_and_b32_e32 v67, 4, v67
	v_lshlrev_b32_e32 v68, 1, v64
	v_and_b32_e32 v68, 8, v68
	v_or3_b32 v66, v66, v67, v68
	v_mul_u32_u24_e32 v66, 0x110, v66
	v_lshl_add_u32 v66, v65, 4, v66
	v_add_u32_e32 v164, 0x4800, v66
	v_bfe_u32 v66, v206, 2, 2
	v_or_b32_e32 v66, v175, v66
	v_mul_u32_u24_e32 v66, 0x120, v66
	v_and_b32_e32 v67, 16, v206
	v_and_b32_e32 v68, 3, v206
	v_lshl_or_b32 v67, v68, 2, v67
	v_lshl_add_u32 v165, v67, 1, v66
	v_lshrrev_b32_e32 v66, 4, v207
	v_and_b32_e32 v67, 15, v207
	v_lshlrev_b32_e32 v67, 4, v67
	v_mul_u32_u24_e32 v68, 0x110, v66
	v_add_u32_e32 v68, v68, v67
	v_add_u32_e32 v166, 0x4800, v68
	v_mul_u32_u24_e32 v68, 0x120, v66
	v_add_u32_e32 v167, v68, v67
	s_waitcnt vmcnt(0)
	v_mul_f32_e32 v179, 0x3fb8aa3b, v179
	v_add_u32_e32 v178, 0x19800, v178
	ds_write_b32 v178, v179
	v_readlane_b32 s46, v251, 19
	v_readlane_b32 s47, v251, 20
	s_mul_i32 s45, s0, 0x2200
	s_add_u32 s24, s45, 0x8c00
	s_add_u32 s25, s45, 0x12c00
	s_cmp_lt_u32 s0, 4
	s_cselect_b32 s45, s24, s25
	s_lshl_b32 s44, s0, 3
	s_waitcnt lgkmcnt(0)
	s_barrier
	s_mov_b32 s3, s1

; #define LDS_WAIT() asm volatile("s_waitcnt lgkmcnt(0)" ::: "memory")
; __device__ __forceinline__ void dsa_unit(const bf16* QB, const int* SEL, bf16* AO, int b, int kvh, int t, LAS unsigned char* wl, int lane) {
;     ...
;     int sidx[8];
; #pragma unroll
;     for (int kb = 0; kb < 8; ++kb) { const int p = 32 * kb + n; sidx[kb] = (p < nsel) ? SEL[row * 256 + p] : 0; }
;     bf16x8 qf[4];
;     { const bf16* qp = QB + row * NBP + CQ + (kvh * 4 + (l15 & 3)) * 128 + 8 * kq;
; #pragma unroll
;       for (int ks = 0; ks < 4; ++ks) qf[ks] = *(const bf16x8*)(qp + 32 * ks); }
;     if (hi == 0) {
; #pragma unroll
;         for (int kb = 0; kb < 8; ++kb) il[32 * kb + n] = sidx[kb];
;     }
;     LDS_WAIT();
;     const int r4 = kq, c16 = l15;
;     const bf16* kg = QB + rowbase * NBP + CK + kvh * 128 + c16 * 8;
;     const bf16* vg = QB + rowbase * NBP + CV + kvh * 128 + c16 * 8;
;     bf16x8 kr[3][8];
; #pragma unroll
;     for (int pb = 0; pb < 3; ++pb)
; #pragma unroll
;         for (int i = 0; i < 8; ++i) kr[pb][i] = *(const bf16x8*)(kg + (size_t)il[32 * pb + 4 * i + r4] * NBP);
.Ldsa_half:
	s_sub_u32 s6, 63, s35
	s_cmp_eq_u32 s21, 0
	s_cselect_b32 s6, s6, s35
	s_lshl_b32 s7, s6, 6
	s_add_u32 s8, s6, 1
	s_lshl_b32 s18, s8, 6
	s_min_u32 s18, s18, 0x100
	s_add_u32 s24, s4, s7
	s_add_u32 s24, s24, s44
	s_lshl_b32 s24, s24, 10
	s_add_u32 s14, s46, s24
	s_addc_u32 s15, s47, 0
	s_add_u32 s40, s14, 0x1000
	s_addc_u32 s41, s15, 0
	s_lshr_b32 s43, s18, 6
	v_lshlrev_b32_e32 v178, 2, v206
	global_load_dword v0, v178, s[14:15] offset:0
	global_load_dword v1, v178, s[14:15] offset:1024
	global_load_dword v2, v178, s[14:15] offset:2048
	global_load_dword v3, v178, s[14:15] offset:3072
	global_load_dword v4, v178, s[40:41] offset:0
	global_load_dword v5, v178, s[40:41] offset:1024
	global_load_dword v6, v178, s[40:41] offset:2048
	global_load_dword v7, v178, s[40:41] offset:3072
	s_cmp_gt_u32 s43, 1
	s_cbranch_scc0 .Ldsa_selld_end
	global_load_dword v8, v178, s[14:15] offset:256
	global_load_dword v9, v178, s[14:15] offset:1280
	global_load_dword v10, v178, s[14:15] offset:2304
	global_load_dword v11, v178, s[14:15] offset:3328
	global_load_dword v12, v178, s[40:41] offset:256
	global_load_dword v13, v178, s[40:41] offset:1280
	global_load_dword v14, v178, s[40:41] offset:2304
	global_load_dword v15, v178, s[40:41] offset:3328
	s_cmp_gt_u32 s43, 2
	s_cbranch_scc0 .Ldsa_selld_end
	global_load_dword v16, v178, s[14:15] offset:512
	global_load_dword v17, v178, s[14:15] offset:1536
	global_load_dword v18, v178, s[14:15] offset:2560
	global_load_dword v19, v178, s[14:15] offset:3584
	global_load_dword v20, v178, s[40:41] offset:512
	global_load_dword v21, v178, s[40:41] offset:1536
	global_load_dword v22, v178, s[40:41] offset:2560
	global_load_dword v23, v178, s[40:41] offset:3584
	s_cmp_gt_u32 s43, 3
	s_cbranch_scc0 .Ldsa_selld_end
	global_load_dword v24, v178, s[14:15] offset:768
	global_load_dword v25, v178, s[14:15] offset:1792
	global_load_dword v26, v178, s[14:15] offset:2816
	global_load_dword v27, v178, s[14:15] offset:3840
	global_load_dword v28, v178, s[40:41] offset:768
	global_load_dword v29, v178, s[40:41] offset:1792
	global_load_dword v30, v178, s[40:41] offset:2816
	global_load_dword v31, v178, s[40:41] offset:3840
.Ldsa_selld_end:
	v_mov_b32_e32 v64, 0
	v_mov_b32_e32 v65, 0
	v_mov_b32_e32 v66, 0
	v_mov_b32_e32 v67, 0
	v_lshlrev_b32_e32 v179, 6, v206
	s_lshl_b32 s24, s0, 12
	s_add_u32 s24, s24, 0x11800
	v_add_u32_e32 v179, s24, v179
	ds_write_b128 v179, v[64:67] offset:0
	ds_write_b128 v179, v[64:67] offset:16
	ds_write_b128 v179, v[64:67] offset:32
	ds_write_b128 v179, v[64:67] offset:48
	v_lshrrev_b32_e32 v178, 4, v207
	v_add_u32_e32 v178, s4, v178
	v_and_b32_e32 v179, 15, v207
	v_lshlrev_b32_e32 v182, 4, v179
	s_lshl_b32 s24, s5, 8
	s_add_u32 s24, s24, 0x1000
	v_add_u32_e32 v182, s24, v182
	v_lshl_add_u64 v[160:161], s[78:79], 0, v[182:183]
	v_mad_u64_u32 v[160:161], s[12:13], v178, s23, v[160:161]
	s_mov_b32 s24, 0x44000
	s_mov_b32 s25, 0
	v_lshl_add_u64 v[162:163], v[160:161], 0, s[24:25]
	global_load_dwordx4 v[144:147], v[160:161], off
	global_load_dwordx4 v[148:151], v[160:161], off offset:1024
	global_load_dwordx4 v[152:155], v[162:163], off
	global_load_dwordx4 v[156:159], v[162:163], off offset:1024
	v_lshl_add_u64 v[160:161], v[160:161], 0, s[16:17]
	v_lshl_add_u64 v[162:163], v[162:163], 0, s[16:17]
	v_and_b32_e32 v64, 31, v206
	v_lshrrev_b32_e32 v65, 2, v64
	v_and_b32_e32 v66, 3, v64
	s_add_u32 s24, s44, s7
	s_add_u32 s24, s24, s4
	v_add_u32_e32 v178, s24, v65
	s_lshl_b32 s25, s5, 2
	v_add_u32_e32 v179, s25, v66
	v_lshlrev_b32_e32 v179, 8, v179
	v_lshl_add_u32 v182, v175, 1, v179
	v_lshl_add_u64 v[128:129], s[78:79], 0, v[182:183]
	v_mad_u64_u32 v[128:129], s[12:13], v178, s23, v[128:129]
	global_load_dwordx4 v[80:83], v[128:129], off offset:0
	global_load_dwordx4 v[84:87], v[128:129], off offset:32
	global_load_dwordx4 v[88:91], v[128:129], off offset:64
	global_load_dwordx4 v[92:95], v[128:129], off offset:96
	global_load_dwordx4 v[96:99], v[128:129], off offset:128
	global_load_dwordx4 v[100:103], v[128:129], off offset:160
	global_load_dwordx4 v[104:107], v[128:129], off offset:192
	global_load_dwordx4 v[108:111], v[128:129], off offset:224
	v_add_u32_e32 v178, s44, v65
	v_lshlrev_b32_e32 v172, 9, v178
	v_add_u32_e32 v172, 0x11800, v172
	s_add_u32 s24, s44, s7
	v_add_u32_e32 v178, s24, v65
	v_sub_u32_e32 v178, v175, v178
	v_add_u32_e32 v178, 0x80, v178
	v_lshlrev_b32_e32 v178, 2, v178
	v_lshl_add_u32 v177, v66, 10, v178
	v_add_u32_e32 v177, 0x1a400, v177
	s_sub_u32 s19, s24, 0x7a
	s_lshl_b32 s25, s5, 2
	v_add_u32_e32 v178, s25, v66
	v_lshlrev_b32_e32 v178, 7, v178
	v_add_u32_e32 v176, 0x1983c, v178
	ds_read_b32 v176, v176
	v_and_b32_e32 v64, 0xff, v207
	v_subrev_u32_e32 v65, 0x80, v64
	v_sub_u32_e32 v66, 0, v65
	v_max_i32_e32 v66, v65, v66
	v_mov_b32_e32 v67, 8
	v_cmp_le_i32_e32 vcc, 12, v66
	s_nop 1
	v_addc_co_u32_e32 v67, vcc, 0, v67, vcc
	v_cmp_le_i32_e32 vcc, 16, v66
	s_nop 1
	v_addc_co_u32_e32 v67, vcc, 0, v67, vcc
	v_cmp_le_i32_e32 vcc, 23, v66
	s_nop 1
	v_addc_co_u32_e32 v67, vcc, 0, v67, vcc
	v_cmp_le_i32_e32 vcc, 32, v66
	s_nop 1
	v_addc_co_u32_e32 v67, vcc, 0, v67, vcc
	v_cmp_le_i32_e32 vcc, 46, v66
	s_nop 1
	v_addc_co_u32_e32 v67, vcc, 0, v67, vcc
	v_cmp_le_i32_e32 vcc, 64, v66
	s_nop 1
	v_addc_co_u32_e32 v67, vcc, 0, v67, vcc
	v_cmp_le_i32_e32 vcc, 91, v66
	s_nop 1
	v_addc_co_u32_e32 v67, vcc, 0, v67, vcc
	v_cmp_gt_i32_e32 vcc, 8, v66
	s_nop 1
	v_cndmask_b32_e32 v67, v67, v66, vcc
	v_add_u32_e32 v68, 16, v67
	v_cmp_lt_i32_e32 vcc, 0, v65
	s_nop 1
	v_cndmask_b32_e32 v67, v67, v68, vcc
	v_lshrrev_b32_e32 v68, 8, v207
	s_lshl_b32 s24, s5, 2
	v_add_u32_e32 v69, s24, v68
	v_lshl_add_u32 v69, v69, 5, v67
	v_lshlrev_b32_e32 v69, 2, v69
	v_add_u32_e32 v69, 0x19800, v69
	ds_read_b32 v70, v69
	ds_read_b32 v71, v69 offset:256
	v_lshl_add_u32 v72, v68, 8, v64
	v_lshlrev_b32_e32 v72, 2, v72
	v_add_u32_e32 v72, 0x1a400, v72
	s_waitcnt lgkmcnt(0)
; __device__ __forceinline__ void dsa_unit(const bf16* QB, const int* SEL, bf16* AO, int b, int kvh, int t, LAS unsigned char* wl, int lane) {
;     ...
;     int sidx[8];
; #pragma unroll
;     for (int kb = 0; kb < 8; ++kb) { const int p = 32 * kb + n; sidx[kb] = (p < nsel) ? SEL[row * 256 + p] : 0; }
;     bf16x8 qf[4];
;     { const bf16* qp = QB + row * NBP + CQ + (kvh * 4 + (l15 & 3)) * 128 + 8 * kq;
; #pragma unroll
;       for (int ks = 0; ks < 4; ++ks) qf[ks] = *(const bf16x8*)(qp + 32 * ks); }
;     if (hi == 0) {
; #pragma unroll
;         for (int kb = 0; kb < 8; ++kb) il[32 * kb + n] = sidx[kb];
	ds_write_b32 v72, v70
	ds_write_b32 v72, v71 offset:2048
	s_waitcnt vmcnt(0)
	s_lshl_b32 s24, s0, 12
	s_add_u32 s24, s24, 0x11800
	v_lshrrev_b32_e32 v64, 3, v0
	v_and_b32_e32 v64, 0x1fc, v64
	v_add_u32_e32 v64, s24, v64
	v_lshlrev_b32_e64 v65, v0, 1
	ds_or_b32 v64, v65 offset:0
	v_lshrrev_b32_e32 v64, 3, v1
	v_and_b32_e32 v64, 0x1fc, v64
	v_add_u32_e32 v64, s24, v64
	v_lshlrev_b32_e64 v65, v1, 1
	ds_or_b32 v64, v65 offset:512
	v_lshrrev_b32_e32 v64, 3, v2
	v_and_b32_e32 v64, 0x1fc, v64
	v_add_u32_e32 v64, s24, v64
	v_lshlrev_b32_e64 v65, v2, 1
	ds_or_b32 v64, v65 offset:1024
	v_lshrrev_b32_e32 v64, 3, v3
	v_and_b32_e32 v64, 0x1fc, v64
	v_add_u32_e32 v64, s24, v64
	v_lshlrev_b32_e64 v65, v3, 1
	ds_or_b32 v64, v65 offset:1536
	v_lshrrev_b32_e32 v64, 3, v4
	v_and_b32_e32 v64, 0x1fc, v64
	v_add_u32_e32 v64, s24, v64
	v_lshlrev_b32_e64 v65, v4, 1
	ds_or_b32 v64, v65 offset:2048
	v_lshrrev_b32_e32 v64, 3, v5
	v_and_b32_e32 v64, 0x1fc, v64
	v_add_u32_e32 v64, s24, v64
	v_lshlrev_b32_e64 v65, v5, 1
	ds_or_b32 v64, v65 offset:2560
	v_lshrrev_b32_e32 v64, 3, v6
	v_and_b32_e32 v64, 0x1fc, v64
	v_add_u32_e32 v64, s24, v64
	v_lshlrev_b32_e64 v65, v6, 1
	ds_or_b32 v64, v65 offset:3072
	v_lshrrev_b32_e32 v64, 3, v7
	v_and_b32_e32 v64, 0x1fc, v64
	v_add_u32_e32 v64, s24, v64
	v_lshlrev_b32_e64 v65, v7, 1
	ds_or_b32 v64, v65 offset:3584
	s_cmp_gt_u32 s43, 1
	s_cbranch_scc0 .Ldsa_selor_end
	v_lshrrev_b32_e32 v64, 3, v8
	v_and_b32_e32 v64, 0x1fc, v64
	v_add_u32_e32 v64, s24, v64
	v_lshlrev_b32_e64 v65, v8, 1
	ds_or_b32 v64, v65 offset:0
	v_lshrrev_b32_e32 v64, 3, v9
	v_and_b32_e32 v64, 0x1fc, v64
	v_add_u32_e32 v64, s24, v64
	v_lshlrev_b32_e64 v65, v9, 1
	ds_or_b32 v64, v65 offset:512
	v_lshrrev_b32_e32 v64, 3, v10
	v_and_b32_e32 v64, 0x1fc, v64
	v_add_u32_e32 v64, s24, v64
	v_lshlrev_b32_e64 v65, v10, 1
	ds_or_b32 v64, v65 offset:1024
	v_lshrrev_b32_e32 v64, 3, v11
	v_and_b32_e32 v64, 0x1fc, v64
	v_add_u32_e32 v64, s24, v64
	v_lshlrev_b32_e64 v65, v11, 1
	ds_or_b32 v64, v65 offset:1536
	v_lshrrev_b32_e32 v64, 3, v12
	v_and_b32_e32 v64, 0x1fc, v64
	v_add_u32_e32 v64, s24, v64
	v_lshlrev_b32_e64 v65, v12, 1
	ds_or_b32 v64, v65 offset:2048
	v_lshrrev_b32_e32 v64, 3, v13
	v_and_b32_e32 v64, 0x1fc, v64
	v_add_u32_e32 v64, s24, v64
	v_lshlrev_b32_e64 v65, v13, 1
	ds_or_b32 v64, v65 offset:2560
	v_lshrrev_b32_e32 v64, 3, v14
	v_and_b32_e32 v64, 0x1fc, v64
	v_add_u32_e32 v64, s24, v64
	v_lshlrev_b32_e64 v65, v14, 1
	ds_or_b32 v64, v65 offset:3072
	v_lshrrev_b32_e32 v64, 3, v15
	v_and_b32_e32 v64, 0x1fc, v64
	v_add_u32_e32 v64, s24, v64
	v_lshlrev_b32_e64 v65, v15, 1
	ds_or_b32 v64, v65 offset:3584
	s_cmp_gt_u32 s43, 2
	s_cbranch_scc0 .Ldsa_selor_end
	v_lshrrev_b32_e32 v64, 3, v16
	v_and_b32_e32 v64, 0x1fc, v64
	v_add_u32_e32 v64, s24, v64
	v_lshlrev_b32_e64 v65, v16, 1
	ds_or_b32 v64, v65 offset:0
	v_lshrrev_b32_e32 v64, 3, v17
	v_and_b32_e32 v64, 0x1fc, v64
	v_add_u32_e32 v64, s24, v64
	v_lshlrev_b32_e64 v65, v17, 1
	ds_or_b32 v64, v65 offset:512
	v_lshrrev_b32_e32 v64, 3, v18
	v_and_b32_e32 v64, 0x1fc, v64
	v_add_u32_e32 v64, s24, v64
	v_lshlrev_b32_e64 v65, v18, 1
	ds_or_b32 v64, v65 offset:1024
	v_lshrrev_b32_e32 v64, 3, v19
	v_and_b32_e32 v64, 0x1fc, v64
	v_add_u32_e32 v64, s24, v64
	v_lshlrev_b32_e64 v65, v19, 1
	ds_or_b32 v64, v65 offset:1536
	v_lshrrev_b32_e32 v64, 3, v20
	v_and_b32_e32 v64, 0x1fc, v64
	v_add_u32_e32 v64, s24, v64
	v_lshlrev_b32_e64 v65, v20, 1
	ds_or_b32 v64, v65 offset:2048
	v_lshrrev_b32_e32 v64, 3, v21
	v_and_b32_e32 v64, 0x1fc, v64
	v_add_u32_e32 v64, s24, v64
	v_lshlrev_b32_e64 v65, v21, 1
	ds_or_b32 v64, v65 offset:2560
	v_lshrrev_b32_e32 v64, 3, v22
	v_and_b32_e32 v64, 0x1fc, v64
	v_add_u32_e32 v64, s24, v64
	v_lshlrev_b32_e64 v65, v22, 1
	ds_or_b32 v64, v65 offset:3072
	v_lshrrev_b32_e32 v64, 3, v23
	v_and_b32_e32 v64, 0x1fc, v64
	v_add_u32_e32 v64, s24, v64
	v_lshlrev_b32_e64 v65, v23, 1
	ds_or_b32 v64, v65 offset:3584
	s_cmp_gt_u32 s43, 3
	s_cbranch_scc0 .Ldsa_selor_end
	v_lshrrev_b32_e32 v64, 3, v24
	v_and_b32_e32 v64, 0x1fc, v64
	v_add_u32_e32 v64, s24, v64
	v_lshlrev_b32_e64 v65, v24, 1
	ds_or_b32 v64, v65 offset:0
	v_lshrrev_b32_e32 v64, 3, v25
	v_and_b32_e32 v64, 0x1fc, v64
	v_add_u32_e32 v64, s24, v64
	v_lshlrev_b32_e64 v65, v25, 1
	ds_or_b32 v64, v65 offset:512
	v_lshrrev_b32_e32 v64, 3, v26
	v_and_b32_e32 v64, 0x1fc, v64
	v_add_u32_e32 v64, s24, v64
	v_lshlrev_b32_e64 v65, v26, 1
	ds_or_b32 v64, v65 offset:1024
	v_lshrrev_b32_e32 v64, 3, v27
	v_and_b32_e32 v64, 0x1fc, v64
	v_add_u32_e32 v64, s24, v64
	v_lshlrev_b32_e64 v65, v27, 1
	ds_or_b32 v64, v65 offset:1536
	v_lshrrev_b32_e32 v64, 3, v28
	v_and_b32_e32 v64, 0x1fc, v64
	v_add_u32_e32 v64, s24, v64
	v_lshlrev_b32_e64 v65, v28, 1
	ds_or_b32 v64, v65 offset:2048
	v_lshrrev_b32_e32 v64, 3, v29
	v_and_b32_e32 v64, 0x1fc, v64
	v_add_u32_e32 v64, s24, v64
	v_lshlrev_b32_e64 v65, v29, 1
	ds_or_b32 v64, v65 offset:2560
	v_lshrrev_b32_e32 v64, 3, v30
	v_and_b32_e32 v64, 0x1fc, v64
	v_add_u32_e32 v64, s24, v64
	v_lshlrev_b32_e64 v65, v30, 1
	ds_or_b32 v64, v65 offset:3072
	v_lshrrev_b32_e32 v64, 3, v31
	v_and_b32_e32 v64, 0x1fc, v64
	v_add_u32_e32 v64, s24, v64
	v_lshlrev_b32_e64 v65, v31, 1
	ds_or_b32 v64, v65 offset:3584
; #define LAS __attribute__((address_space(3)))
; #define LDS_WAIT() asm volatile("s_waitcnt lgkmcnt(0)" ::: "memory")
; __device__ __forceinline__ void dsa_unit(const bf16* QB, const int* SEL, bf16* AO, int b, int kvh, int t, LAS unsigned char* wl, int lane) {
;     ...
;         for (int i = 0; i < 8; ++i) *(LAS bf16x8*)(kdst + (4 * i) * 272) = kr[kb % 3][i];
;         if (kb + 3 < 8) {
; #pragma unroll
;             for (int i = 0; i < 8; ++i) kr[kb % 3][i] = *(const bf16x8*)(kg + (size_t)il[32 * (kb + 3) + 4 * i + r4] * NBP);
;         }
;         LDS_WAIT();
;         f32x4v a0 = {0.f, 0.f, 0.f, 0.f}, a1 = {0.f, 0.f, 0.f, 0.f};
; #pragma unroll
;         for (int ks = 0; ks < 4; ++ks) { const bf16x8 b0 = *(const LAS bf16x8*)(kfb + 64 * ks), b1 = *(const LAS bf16x8*)(kfb + 16 * 272 + 64 * ks);
;             a0 = __builtin_amdgcn_mfma_f32_16x16x32_bf16(qf[ks], b0, a0, 0, 0, 0); a1 = __builtin_amdgcn_mfma_f32_16x16x32_bf16(qf[ks], b1, a1, 0, 0, 0); }
;         LDS_WAIT();
;         const int bk = t5_bucket(sidx[kb] - t);
;         const bool valid = (32 * kb + n) < nsel;
; #pragma unroll
;         for (int g = 0; g < 4; ++g) { const float raw = upper ? a1[g] : a0[g]; const float v = valid ? raw + bl[g * 32 + bk] : -__builtin_inff(); lg[kb][g] = v; mx[g] = __builtin_fmaxf(mx[g], v); }
;     ...
;     f32x4v o[8];
; #pragma unroll
;     for (int c = 0; c < 8; ++c) o[c] = (f32x4v){0.f, 0.f, 0.f, 0.f};
.Ldsa_selor_end:
	ds_write_b128 v166, v[144:147]
	ds_write_b128 v167, v[148:151]
	ds_write_b128 v166, v[152:155] offset:8704
	ds_write_b128 v167, v[156:159] offset:9216
	v_mov_b32_e32 v0, 0
	v_mov_b32_e32 v1, 0
	v_mov_b32_e32 v2, 0
	v_mov_b32_e32 v3, 0
	v_mov_b32_e32 v4, 0
	v_mov_b32_e32 v5, 0
	v_mov_b32_e32 v6, 0
	v_mov_b32_e32 v7, 0
	v_mov_b32_e32 v8, 0
	v_mov_b32_e32 v9, 0
	v_mov_b32_e32 v10, 0
	v_mov_b32_e32 v11, 0
	v_mov_b32_e32 v12, 0
	v_mov_b32_e32 v13, 0
	v_mov_b32_e32 v14, 0
	v_mov_b32_e32 v15, 0
	v_mov_b32_e32 v16, 0
	v_mov_b32_e32 v17, 0
	v_mov_b32_e32 v18, 0
	v_mov_b32_e32 v19, 0
	v_mov_b32_e32 v20, 0
	v_mov_b32_e32 v21, 0
	v_mov_b32_e32 v22, 0
	v_mov_b32_e32 v23, 0
	v_mov_b32_e32 v24, 0
	v_mov_b32_e32 v25, 0
	v_mov_b32_e32 v26, 0
	v_mov_b32_e32 v27, 0
	v_mov_b32_e32 v28, 0
	v_mov_b32_e32 v29, 0
	v_mov_b32_e32 v30, 0
	v_mov_b32_e32 v31, 0
	v_mov_b32_e32 v32, 0
	v_mov_b32_e32 v33, 0
	v_mov_b32_e32 v34, 0
	v_mov_b32_e32 v35, 0
	v_mov_b32_e32 v36, 0
	v_mov_b32_e32 v37, 0
	v_mov_b32_e32 v38, 0
	v_mov_b32_e32 v39, 0
	v_mov_b32_e32 v40, 0
	v_mov_b32_e32 v41, 0
	v_mov_b32_e32 v42, 0
	v_mov_b32_e32 v43, 0
	v_mov_b32_e32 v44, 0
	v_mov_b32_e32 v45, 0
	v_mov_b32_e32 v46, 0
	v_mov_b32_e32 v47, 0
	v_mov_b32_e32 v48, 0
	v_mov_b32_e32 v49, 0
	v_mov_b32_e32 v50, 0
	v_mov_b32_e32 v51, 0
	v_mov_b32_e32 v52, 0
	v_mov_b32_e32 v53, 0
	v_mov_b32_e32 v54, 0
	v_mov_b32_e32 v55, 0
	v_mov_b32_e32 v56, 0
	v_mov_b32_e32 v57, 0
	v_mov_b32_e32 v58, 0
	v_mov_b32_e32 v59, 0
	v_mov_b32_e32 v60, 0
	v_mov_b32_e32 v61, 0
	v_mov_b32_e32 v62, 0
	v_mov_b32_e32 v63, 0
	v_mov_b32_e32 v173, 0
	s_mov_b32 s9, 0
	s_mov_b32 s10, 0
	s_mov_b32 s11, 0x8c00
	s_waitcnt lgkmcnt(0)
	s_barrier
	s_mov_b32 s13, 0xf149f2ca
	ds_read_b32 v174, v172
	ds_read_b32 v182, v172 offset:4
	s_waitcnt lgkmcnt(0)
	v_lshrrev_b32_e32 v174, v175, v174
	v_bfe_i32 v178, v174, 0, 1
	v_bfi_b32 v64, v178, v176, s13
	v_bfe_i32 v179, v174, 1, 1
	v_bfi_b32 v65, v179, v176, s13
	v_bfe_i32 v178, v174, 2, 1
	v_bfi_b32 v66, v178, v176, s13
	v_bfe_i32 v179, v174, 3, 1
	v_bfi_b32 v67, v179, v176, s13
	v_bfe_i32 v178, v174, 4, 1
	v_bfi_b32 v68, v178, v176, s13
	v_bfe_i32 v179, v174, 5, 1
	v_bfi_b32 v69, v179, v176, s13
	v_bfe_i32 v178, v174, 6, 1
	v_bfi_b32 v70, v178, v176, s13
	v_bfe_i32 v179, v174, 7, 1
	v_bfi_b32 v71, v179, v176, s13
	v_bfe_i32 v178, v174, 16, 1
	v_bfi_b32 v72, v178, v176, s13
	v_bfe_i32 v179, v174, 17, 1
	v_bfi_b32 v73, v179, v176, s13
	v_bfe_i32 v178, v174, 18, 1
	v_bfi_b32 v74, v178, v176, s13
	v_bfe_i32 v179, v174, 19, 1
	v_bfi_b32 v75, v179, v176, s13
	v_bfe_i32 v178, v174, 20, 1
	v_bfi_b32 v76, v178, v176, s13
	v_bfe_i32 v179, v174, 21, 1
	v_bfi_b32 v77, v179, v176, s13
	v_bfe_i32 v178, v174, 22, 1
	v_bfi_b32 v78, v178, v176, s13
	v_bfe_i32 v179, v174, 23, 1
	v_bfi_b32 v79, v179, v176, s13

; #define LAS __attribute__((address_space(3)))
; __device__ __forceinline__ unsigned pk2(float lo, float hi) { return pg8::cvt_pk_bf16(lo, hi); }
; #define LDS_WAIT() asm volatile("s_waitcnt lgkmcnt(0)" ::: "memory")
; __device__ __forceinline__ s16x4 vtr(const LAS unsigned char* p) { return __builtin_bit_cast(s16x4, __builtin_amdgcn_ds_read_tr16_b64_v4i16((LAS s16x4*)p)); }
; __device__ __forceinline__ void dsa_unit(const bf16* QB, const int* SEL, bf16* AO, int b, int kvh, int t, LAS unsigned char* wl, int lane) {
;     ...
; #pragma unroll
;     for (int g = 0; g < 4; ++g) {
;         float m = mx[g];
;         m = __builtin_fmaxf(m, __shfl_xor(m, 1)); m = __builtin_fmaxf(m, __shfl_xor(m, 2)); m = __builtin_fmaxf(m, __shfl_xor(m, 4)); m = __builtin_fmaxf(m, __shfl_xor(m, 8)); m = __builtin_fmaxf(m, __shfl_xor(m, 16));
;         float s = 0.f;
; #pragma unroll
;         for (int kb = 0; kb < 8; ++kb) { const float e = __builtin_amdgcn_exp2f(lg[kb][g] - m); lg[kb][g] = e; s += e; }
;         s += __shfl_xor(s, 1); s += __shfl_xor(s, 2); s += __shfl_xor(s, 4); s += __shfl_xor(s, 8); s += __shfl_xor(s, 16);
;         const float inv = 1.0f / s;
; #pragma unroll
;         for (int kb = 0; kb < 8; ++kb) if ((kb >> 2) == hi) pT[g * 256 + 32 * kb + n] = (bf16)(pk2(lg[kb][g] * inv, 0.f) & 0xffffu);
;     }
;     f32x4v o[8];
; #pragma unroll
;     for (int c = 0; c < 8; ++c) o[c] = (f32x4v){0.f, 0.f, 0.f, 0.f};
;     const LAS unsigned char* vtb = buf + (8 * kq + (l15 >> 2)) * 288 + (lane & 3) * 8;
;     LAS unsigned char* vdst = buf + r4 * 288 + c16 * 16;
;     const LAS bf16* pfp = pT + (l15 & 3) * 256 + 8 * kq;
; #pragma unroll
;     for (int ch = 0; ch < 8; ++ch) {
; #pragma unroll
;         for (int i = 0; i < 8; ++i) *(LAS bf16x8*)(vdst + (4 * i) * 288) = vr[ch % 3][i];
;         if (ch + 3 < 8) {
; #pragma unroll
;             for (int i = 0; i < 8; ++i) vr[ch % 3][i] = *(const bf16x8*)(vg + (size_t)il[32 * (ch + 3) + 4 * i + r4] * NBP);
;         }
;         const bf16x8 pf = *(const LAS bf16x8*)(pfp + 32 * ch);
;         LDS_WAIT();
; #pragma unroll
;         for (int c = 0; c < 8; ++c) {
;             const s16x4 lo = vtr(vtb + c * 32), hh = vtr(vtb + 4 * 288 + c * 32);
;             o[c] = __builtin_amdgcn_mfma_f32_16x16x32_bf16(pf, (bf16x8){lo[0], lo[1], lo[2], lo[3], hh[0], hh[1], hh[2], hh[3]}, o[c], 0, 0, 0);
;         }
.Ldsa_farB:
	ds_read_b32 v174, v172 offset:8
	ds_read_b32 v182, v172 offset:12
	s_nop 1
	s_waitcnt lgkmcnt(5)
	v_mfma_f32_32x32x16_bf16 v[128:143], v[112:115], v[80:83], v[128:143]
	ds_read_b128 v[112:115], v168 offset:8832
	v_exp_f32_e32 v64, v64
	v_exp_f32_e32 v65, v65
	v_add_f32_e32 v173, v173, v64
	v_add_f32_e32 v173, v173, v65
	v_cvt_pk_bf16_f32 v64, v64, v65
	s_waitcnt lgkmcnt(5)
	v_mfma_f32_32x32x16_bf16 v[128:143], v[116:119], v[84:87], v[128:143]
	ds_read_b128 v[116:119], v168 offset:8864
	v_exp_f32_e32 v66, v66
	v_exp_f32_e32 v67, v67
	v_add_f32_e32 v173, v173, v66
	v_add_f32_e32 v173, v173, v67
	v_cvt_pk_bf16_f32 v65, v66, v67
	s_waitcnt lgkmcnt(5)
	v_mfma_f32_32x32x16_bf16 v[128:143], v[120:123], v[88:91], v[128:143]
	ds_read_b128 v[120:123], v168 offset:8896
	v_exp_f32_e32 v68, v68
	v_exp_f32_e32 v69, v69
	v_add_f32_e32 v173, v173, v68
	v_add_f32_e32 v173, v173, v69
	v_cvt_pk_bf16_f32 v66, v68, v69
	s_waitcnt lgkmcnt(5)
	v_mfma_f32_32x32x16_bf16 v[128:143], v[124:127], v[92:95], v[128:143]
	ds_read_b128 v[124:127], v168 offset:8928
	v_exp_f32_e32 v70, v70
	v_exp_f32_e32 v71, v71
	v_add_f32_e32 v173, v173, v70
	v_add_f32_e32 v173, v173, v71
	v_cvt_pk_bf16_f32 v67, v70, v71
	s_waitcnt lgkmcnt(3)
	v_mfma_f32_32x32x16_bf16 v[128:143], v[112:115], v[96:99], v[128:143]
	ds_read_b64_tr_b16 v[112:113], v169 offset:0
	ds_read_b64_tr_b16 v[114:115], v169 offset:1152
	v_exp_f32_e32 v72, v72
	v_exp_f32_e32 v73, v73
	v_add_f32_e32 v173, v173, v72
	v_add_f32_e32 v173, v173, v73
	v_cvt_pk_bf16_f32 v68, v72, v73
	s_waitcnt lgkmcnt(4)
	v_mfma_f32_32x32x16_bf16 v[128:143], v[116:119], v[100:103], v[128:143]
	ds_read_b64_tr_b16 v[116:117], v169 offset:64
	ds_read_b64_tr_b16 v[118:119], v169 offset:1216
	v_exp_f32_e32 v74, v74
	v_exp_f32_e32 v75, v75
	v_add_f32_e32 v173, v173, v74
	v_add_f32_e32 v173, v173, v75
	v_cvt_pk_bf16_f32 v69, v74, v75
	s_waitcnt lgkmcnt(5)
	v_mfma_f32_32x32x16_bf16 v[128:143], v[120:123], v[104:107], v[128:143]
	ds_read_b64_tr_b16 v[120:121], v169 offset:128
	ds_read_b64_tr_b16 v[122:123], v169 offset:1280
	v_exp_f32_e32 v76, v76
	v_exp_f32_e32 v77, v77
	v_add_f32_e32 v173, v173, v76
	v_add_f32_e32 v173, v173, v77
	v_cvt_pk_bf16_f32 v70, v76, v77
	s_waitcnt lgkmcnt(6)
	v_mfma_f32_32x32x16_bf16 v[128:143], v[124:127], v[108:111], v[128:143]
	ds_read_b64_tr_b16 v[124:125], v169 offset:192
	ds_read_b64_tr_b16 v[126:127], v169 offset:1344
	v_exp_f32_e32 v78, v78
	v_exp_f32_e32 v79, v79
	v_add_f32_e32 v173, v173, v78
	v_add_f32_e32 v173, v173, v79
	v_cvt_pk_bf16_f32 v71, v78, v79
	s_waitcnt lgkmcnt(6)
	v_mfma_f32_32x32x16_bf16 v[0:15], v[64:67], v[112:115], v[0:15]
	ds_read_b64_tr_b16 v[112:113], v169 offset:4608
	ds_read_b64_tr_b16 v[114:115], v169 offset:5760
	s_waitcnt vmcnt(0)
	ds_write_b128 v170, v[144:147]
	v_exp_f32_e32 v128, v128
	v_exp_f32_e32 v129, v129
	v_add_f32_e32 v173, v173, v128
	v_add_f32_e32 v173, v173, v129
	v_cvt_pk_bf16_f32 v128, v128, v129
	s_waitcnt lgkmcnt(7)
	v_mfma_f32_32x32x16_bf16 v[16:31], v[64:67], v[116:119], v[16:31]
	ds_read_b64_tr_b16 v[116:117], v169 offset:4672
	ds_read_b64_tr_b16 v[118:119], v169 offset:5824
	ds_write_b128 v171, v[148:151]
	v_exp_f32_e32 v130, v130
	v_exp_f32_e32 v131, v131
	v_add_f32_e32 v173, v173, v130
	v_add_f32_e32 v173, v173, v131
	v_cvt_pk_bf16_f32 v129, v130, v131
	s_waitcnt lgkmcnt(8)
	v_mfma_f32_32x32x16_bf16 v[32:47], v[64:67], v[120:123], v[32:47]
	ds_read_b64_tr_b16 v[120:121], v169 offset:4736
	ds_read_b64_tr_b16 v[122:123], v169 offset:5888
	ds_write_b128 v170, v[152:155] offset:8704
	v_exp_f32_e32 v132, v132
	v_exp_f32_e32 v133, v133
	v_add_f32_e32 v173, v173, v132
	v_add_f32_e32 v173, v173, v133
	v_cvt_pk_bf16_f32 v130, v132, v133
	s_waitcnt lgkmcnt(9)
	v_mfma_f32_32x32x16_bf16 v[48:63], v[64:67], v[124:127], v[48:63]
	ds_read_b64_tr_b16 v[124:125], v169 offset:4800
	ds_read_b64_tr_b16 v[126:127], v169 offset:5952
	ds_write_b128 v171, v[156:159] offset:9216
	v_exp_f32_e32 v134, v134
	v_exp_f32_e32 v135, v135
	v_add_f32_e32 v173, v173, v134
	v_add_f32_e32 v173, v173, v135
	v_cvt_pk_bf16_f32 v131, v134, v135
	s_waitcnt lgkmcnt(10)
	v_mfma_f32_32x32x16_bf16 v[0:15], v[68:71], v[112:115], v[0:15]
	ds_read_b64_tr_b16 v[112:113], v169 offset:9216
	ds_read_b64_tr_b16 v[114:115], v169 offset:10368
	s_nop 0
	v_exp_f32_e32 v136, v136
	v_exp_f32_e32 v137, v137
	v_add_f32_e32 v173, v173, v136
	v_add_f32_e32 v173, v173, v137
	v_cvt_pk_bf16_f32 v132, v136, v137
	s_waitcnt lgkmcnt(9)
	v_mfma_f32_32x32x16_bf16 v[16:31], v[68:71], v[116:119], v[16:31]
	ds_read_b64_tr_b16 v[116:117], v169 offset:9280
	ds_read_b64_tr_b16 v[118:119], v169 offset:10432
	s_nop 0
	v_exp_f32_e32 v138, v138
	v_exp_f32_e32 v139, v139
	v_add_f32_e32 v173, v173, v138
	v_add_f32_e32 v173, v173, v139
	v_cvt_pk_bf16_f32 v133, v138, v139
	s_waitcnt lgkmcnt(8)
	v_mfma_f32_32x32x16_bf16 v[32:47], v[68:71], v[120:123], v[32:47]
	ds_read_b64_tr_b16 v[120:121], v169 offset:9344
	ds_read_b64_tr_b16 v[122:123], v169 offset:10496
	s_nop 0
	v_exp_f32_e32 v140, v140
	v_exp_f32_e32 v141, v141
	v_add_f32_e32 v173, v173, v140
	v_add_f32_e32 v173, v173, v141
	v_cvt_pk_bf16_f32 v134, v140, v141
	s_waitcnt lgkmcnt(7)
	v_mfma_f32_32x32x16_bf16 v[48:63], v[68:71], v[124:127], v[48:63]
	ds_read_b64_tr_b16 v[124:125], v169 offset:9408
	ds_read_b64_tr_b16 v[126:127], v169 offset:10560
	s_nop 0
	v_exp_f32_e32 v142, v142
	v_exp_f32_e32 v143, v143
	v_add_f32_e32 v173, v173, v142
	v_add_f32_e32 v173, v173, v143
	v_cvt_pk_bf16_f32 v135, v142, v143
	v_lshrrev_b32_e32 v174, v175, v174
	s_waitcnt lgkmcnt(6)
; #define LAS __attribute__((address_space(3)))
; #define LDS_WAIT() asm volatile("s_waitcnt lgkmcnt(0)" ::: "memory")
; __device__ __forceinline__ s16x4 vtr(const LAS unsigned char* p) { return __builtin_bit_cast(s16x4, __builtin_amdgcn_ds_read_tr16_b64_v4i16((LAS s16x4*)p)); }
; __device__ __forceinline__ void dsa_unit(const bf16* QB, const int* SEL, bf16* AO, int b, int kvh, int t, LAS unsigned char* wl, int lane) {
;     ...
;     for (int ch = 0; ch < 8; ++ch) {
; #pragma unroll
;         for (int i = 0; i < 8; ++i) *(LAS bf16x8*)(vdst + (4 * i) * 288) = vr[ch % 3][i];
;         if (ch + 3 < 8) {
; #pragma unroll
;             for (int i = 0; i < 8; ++i) vr[ch % 3][i] = *(const bf16x8*)(vg + (size_t)il[32 * (ch + 3) + 4 * i + r4] * NBP);
;         }
;         const bf16x8 pf = *(const LAS bf16x8*)(pfp + 32 * ch);
;         LDS_WAIT();
; #pragma unroll
;         for (int c = 0; c < 8; ++c) {
;             const s16x4 lo = vtr(vtb + c * 32), hh = vtr(vtb + 4 * 288 + c * 32);
;             o[c] = __builtin_amdgcn_mfma_f32_16x16x32_bf16(pf, (bf16x8){lo[0], lo[1], lo[2], lo[3], hh[0], hh[1], hh[2], hh[3]}, o[c], 0, 0, 0);
;         }
;         LDS_WAIT();
;     }
;     bf16* op = AO + row * D + (kvh * 4) * 128 + 16 * kq + l15;
	v_mfma_f32_32x32x16_bf16 v[0:15], v[128:131], v[112:115], v[0:15]
	ds_read_b64_tr_b16 v[112:113], v169 offset:13824
	ds_read_b64_tr_b16 v[114:115], v169 offset:14976
	v_bfe_i32 v178, v174, 0, 1
	v_bfi_b32 v64, v178, v176, s13
	v_bfe_i32 v179, v174, 1, 1
	v_bfi_b32 v65, v179, v176, s13
	s_waitcnt lgkmcnt(6)
	v_mfma_f32_32x32x16_bf16 v[16:31], v[128:131], v[116:119], v[16:31]
	ds_read_b64_tr_b16 v[116:117], v169 offset:13888
	ds_read_b64_tr_b16 v[118:119], v169 offset:15040
	v_bfe_i32 v178, v174, 2, 1
	v_bfi_b32 v66, v178, v176, s13
	v_bfe_i32 v179, v174, 3, 1
	v_bfi_b32 v67, v179, v176, s13
	s_waitcnt lgkmcnt(6)
	v_mfma_f32_32x32x16_bf16 v[32:47], v[128:131], v[120:123], v[32:47]
	ds_read_b64_tr_b16 v[120:121], v169 offset:13952
	ds_read_b64_tr_b16 v[122:123], v169 offset:15104
	v_bfe_i32 v178, v174, 4, 1
	v_bfi_b32 v68, v178, v176, s13
	v_bfe_i32 v179, v174, 5, 1
	v_bfi_b32 v69, v179, v176, s13
	s_waitcnt lgkmcnt(6)
	v_mfma_f32_32x32x16_bf16 v[48:63], v[128:131], v[124:127], v[48:63]
	ds_read_b64_tr_b16 v[124:125], v169 offset:14016
	ds_read_b64_tr_b16 v[126:127], v169 offset:15168
	v_bfe_i32 v178, v174, 6, 1
	v_bfi_b32 v70, v178, v176, s13
	v_bfe_i32 v179, v174, 7, 1
	v_bfi_b32 v71, v179, v176, s13
	s_waitcnt lgkmcnt(6)
	v_mfma_f32_32x32x16_bf16 v[0:15], v[132:135], v[112:115], v[0:15]
	v_bfe_i32 v178, v174, 16, 1
	v_bfi_b32 v72, v178, v176, s13
	v_bfe_i32 v179, v174, 17, 1
	v_bfi_b32 v73, v179, v176, s13
	s_waitcnt lgkmcnt(4)
	v_mfma_f32_32x32x16_bf16 v[16:31], v[132:135], v[116:119], v[16:31]
	v_bfe_i32 v178, v174, 18, 1
	v_bfi_b32 v74, v178, v176, s13
	v_bfe_i32 v179, v174, 19, 1
	v_bfi_b32 v75, v179, v176, s13
	s_waitcnt lgkmcnt(2)
	v_mfma_f32_32x32x16_bf16 v[32:47], v[132:135], v[120:123], v[32:47]
	v_bfe_i32 v178, v174, 20, 1
	v_bfi_b32 v76, v178, v176, s13
	v_bfe_i32 v179, v174, 21, 1
	v_bfi_b32 v77, v179, v176, s13
	s_waitcnt lgkmcnt(0)
	v_mfma_f32_32x32x16_bf16 v[48:63], v[132:135], v[124:127], v[48:63]
	v_bfe_i32 v178, v174, 22, 1
	v_bfi_b32 v78, v178, v176, s13
	v_bfe_i32 v179, v174, 23, 1
	v_bfi_b32 v79, v179, v176, s13
	s_waitcnt lgkmcnt(0)
	s_barrier
	s_mov_b32 s25, s10
	s_mov_b32 s10, s11
	s_mov_b32 s11, s25
	v_add_u32_e32 v172, 8, v172
	s_mov_b32 s9, s24
	s_cmp_lt_u32 s9, s8
	s_cbranch_scc1 .Ldsa_it
	v_xor_b32_e32 v178, 32, v206
	v_lshlrev_b32_e32 v178, 2, v178
	ds_bpermute_b32 v179, v178, v173
	s_waitcnt lgkmcnt(0)
	v_add_f32_e32 v173, v173, v179
	v_rcp_f32_e32 v173, v173
	s_nop 0
	v_and_b32_e32 v178, 31, v206
	v_lshlrev_b32_e32 v178, 2, v178
	s_lshl_b32 s24, s0, 7
	s_add_u32 s24, s24, 0x1a000
	v_add_u32_e32 v178, s24, v178
	ds_write_b32 v178, v173
	v_lshl_add_u32 v179, v175, 1, s24
	s_waitcnt lgkmcnt(0)
	ds_read_b128 v[112:115], v179 offset:0
	ds_read_b128 v[116:119], v179 offset:32
	ds_read_b128 v[120:123], v179 offset:64
	ds_read_b128 v[124:127], v179 offset:96
	v_and_b32_e32 v178, 31, v206
	v_lshlrev_b32_e32 v178, 1, v178
	v_mul_u32_u24_e32 v179, 0x88, v175
	v_add3_u32 v178, v178, v179, s45
	v_lshrrev_b32_e32 v179, 4, v206
	v_mul_u32_u24_e32 v182, 0x110, v179
	v_and_b32_e32 v172, 15, v206
	v_lshl_add_u32 v182, v172, 4, v182
	v_add_u32_e32 v174, s45, v182
	s_add_u32 s24, s44, s7
	s_add_u32 s24, s24, s4
	s_lshr_b32 s25, s24, 20
	s_lshl_b32 s24, s24, 12
	s_add_u32 s24, s24, s67
	s_addc_u32 s25, s25, s85
	s_lshl_b32 s26, s5, 10
	s_add_u32 s24, s24, s26
	s_addc_u32 s25, s25, 0
	v_lshlrev_b32_e32 v179, 8, v179
	v_lshl_add_u32 v182, v172, 4, v179
	v_lshl_add_u64 v[144:145], s[24:25], 0, v[182:183]
	s_movk_i32 s26, 0x1000
	s_mov_b32 s27, 0
	s_waitcnt lgkmcnt(0)
; __device__ __forceinline__ unsigned pk2(float lo, float hi) { return pg8::cvt_pk_bf16(lo, hi); }
; __device__ __forceinline__ void dsa_unit(const bf16* QB, const int* SEL, bf16* AO, int b, int kvh, int t, LAS unsigned char* wl, int lane) {
;     ...
;     bf16* op = AO + row * D + (kvh * 4) * 128 + 16 * kq + l15;
; #pragma unroll
;     for (int i = 0; i < 2; ++i)
; #pragma unroll
;         for (int g = 0; g < 4; ++g) {
;             const float v = (kq == 0) ? o[4 * i][g] : (kq == 1) ? o[4 * i + 1][g] : (kq == 2) ? o[4 * i + 2][g] : o[4 * i + 3][g];
;             op[g * 128 + 64 * i] = (bf16)(pk2(v, 0.f) & 0xffffu);
;         }
	v_pk_mul_f32 v[0:1], v[0:1], v[112:113]
	v_pk_mul_f32 v[2:3], v[2:3], v[114:115]
	v_pk_mul_f32 v[4:5], v[4:5], v[116:117]
	v_pk_mul_f32 v[6:7], v[6:7], v[118:119]
	v_pk_mul_f32 v[8:9], v[8:9], v[120:121]
	v_pk_mul_f32 v[10:11], v[10:11], v[122:123]
	v_pk_mul_f32 v[12:13], v[12:13], v[124:125]
	v_pk_mul_f32 v[14:15], v[14:15], v[126:127]
	v_pk_mul_f32 v[16:17], v[16:17], v[112:113]
	v_pk_mul_f32 v[18:19], v[18:19], v[114:115]
	v_pk_mul_f32 v[20:21], v[20:21], v[116:117]
	v_pk_mul_f32 v[22:23], v[22:23], v[118:119]
	v_pk_mul_f32 v[24:25], v[24:25], v[120:121]
	v_pk_mul_f32 v[26:27], v[26:27], v[122:123]
	v_pk_mul_f32 v[28:29], v[28:29], v[124:125]
	v_pk_mul_f32 v[30:31], v[30:31], v[126:127]
	v_pk_mul_f32 v[32:33], v[32:33], v[112:113]
	v_pk_mul_f32 v[34:35], v[34:35], v[114:115]
	v_pk_mul_f32 v[36:37], v[36:37], v[116:117]
	v_pk_mul_f32 v[38:39], v[38:39], v[118:119]
	v_pk_mul_f32 v[40:41], v[40:41], v[120:121]
	v_pk_mul_f32 v[42:43], v[42:43], v[122:123]
	v_pk_mul_f32 v[44:45], v[44:45], v[124:125]
	v_pk_mul_f32 v[46:47], v[46:47], v[126:127]
	v_pk_mul_f32 v[48:49], v[48:49], v[112:113]
	v_pk_mul_f32 v[50:51], v[50:51], v[114:115]
	v_pk_mul_f32 v[52:53], v[52:53], v[116:117]
	v_pk_mul_f32 v[54:55], v[54:55], v[118:119]
	v_pk_mul_f32 v[56:57], v[56:57], v[120:121]
	v_pk_mul_f32 v[58:59], v[58:59], v[122:123]
	v_pk_mul_f32 v[60:61], v[60:61], v[124:125]
	v_pk_mul_f32 v[62:63], v[62:63], v[126:127]
	v_cvt_pk_bf16_f32 v64, v0, v1
	v_cvt_pk_bf16_f32 v65, v2, v3
	v_cvt_pk_bf16_f32 v66, v4, v5
	v_cvt_pk_bf16_f32 v67, v6, v7
	v_cvt_pk_bf16_f32 v68, v8, v9
	v_cvt_pk_bf16_f32 v69, v10, v11
	v_cvt_pk_bf16_f32 v70, v12, v13
	v_cvt_pk_bf16_f32 v71, v14, v15
	ds_write_b16 v178, v64 offset:0
	ds_write_b16_d16_hi v178, v64 offset:272
	ds_write_b16 v178, v65 offset:544
	ds_write_b16_d16_hi v178, v65 offset:816
	ds_write_b16 v178, v66 offset:2176
	ds_write_b16_d16_hi v178, v66 offset:2448
	ds_write_b16 v178, v67 offset:2720
	ds_write_b16_d16_hi v178, v67 offset:2992
	ds_write_b16 v178, v68 offset:4352
	ds_write_b16_d16_hi v178, v68 offset:4624
	ds_write_b16 v178, v69 offset:4896
	ds_write_b16_d16_hi v178, v69 offset:5168
	ds_write_b16 v178, v70 offset:6528
	ds_write_b16_d16_hi v178, v70 offset:6800
	ds_write_b16 v178, v71 offset:7072
	ds_write_b16_d16_hi v178, v71 offset:7344
	v_cvt_pk_bf16_f32 v72, v16, v17
	v_cvt_pk_bf16_f32 v73, v18, v19
	v_cvt_pk_bf16_f32 v74, v20, v21
	v_cvt_pk_bf16_f32 v75, v22, v23
	v_cvt_pk_bf16_f32 v76, v24, v25
	v_cvt_pk_bf16_f32 v77, v26, v27
	v_cvt_pk_bf16_f32 v78, v28, v29
	v_cvt_pk_bf16_f32 v79, v30, v31
	ds_write_b16 v178, v72 offset:64
	ds_write_b16_d16_hi v178, v72 offset:336
	ds_write_b16 v178, v73 offset:608
	ds_write_b16_d16_hi v178, v73 offset:880
	ds_write_b16 v178, v74 offset:2240
	ds_write_b16_d16_hi v178, v74 offset:2512
	ds_write_b16 v178, v75 offset:2784
	ds_write_b16_d16_hi v178, v75 offset:3056
	ds_write_b16 v178, v76 offset:4416
	ds_write_b16_d16_hi v178, v76 offset:4688
	ds_write_b16 v178, v77 offset:4960
	ds_write_b16_d16_hi v178, v77 offset:5232
	ds_write_b16 v178, v78 offset:6592
	ds_write_b16_d16_hi v178, v78 offset:6864
	ds_write_b16 v178, v79 offset:7136
	ds_write_b16_d16_hi v178, v79 offset:7408
	v_cvt_pk_bf16_f32 v128, v32, v33
	v_cvt_pk_bf16_f32 v129, v34, v35
	v_cvt_pk_bf16_f32 v130, v36, v37
	v_cvt_pk_bf16_f32 v131, v38, v39
	v_cvt_pk_bf16_f32 v132, v40, v41
	v_cvt_pk_bf16_f32 v133, v42, v43
	v_cvt_pk_bf16_f32 v134, v44, v45
	v_cvt_pk_bf16_f32 v135, v46, v47
	ds_write_b16 v178, v128 offset:128
	ds_write_b16_d16_hi v178, v128 offset:400
	ds_write_b16 v178, v129 offset:672
	ds_write_b16_d16_hi v178, v129 offset:944
	ds_write_b16 v178, v130 offset:2304
	ds_write_b16_d16_hi v178, v130 offset:2576
	ds_write_b16 v178, v131 offset:2848
	ds_write_b16_d16_hi v178, v131 offset:3120
	ds_write_b16 v178, v132 offset:4480
	ds_write_b16_d16_hi v178, v132 offset:4752
	ds_write_b16 v178, v133 offset:5024
	ds_write_b16_d16_hi v178, v133 offset:5296
	ds_write_b16 v178, v134 offset:6656
	ds_write_b16_d16_hi v178, v134 offset:6928
	ds_write_b16 v178, v135 offset:7200
	ds_write_b16_d16_hi v178, v135 offset:7472
	v_cvt_pk_bf16_f32 v136, v48, v49
	v_cvt_pk_bf16_f32 v137, v50, v51
	v_cvt_pk_bf16_f32 v138, v52, v53
	v_cvt_pk_bf16_f32 v139, v54, v55
	v_cvt_pk_bf16_f32 v140, v56, v57
	v_cvt_pk_bf16_f32 v141, v58, v59
	v_cvt_pk_bf16_f32 v142, v60, v61
	v_cvt_pk_bf16_f32 v143, v62, v63
	ds_write_b16 v178, v136 offset:192
	ds_write_b16_d16_hi v178, v136 offset:464
	ds_write_b16 v178, v137 offset:736
	ds_write_b16_d16_hi v178, v137 offset:1008
	ds_write_b16 v178, v138 offset:2368
	ds_write_b16_d16_hi v178, v138 offset:2640
	ds_write_b16 v178, v139 offset:2912
	ds_write_b16_d16_hi v178, v139 offset:3184
	ds_write_b16 v178, v140 offset:4544
	ds_write_b16_d16_hi v178, v140 offset:4816
	ds_write_b16 v178, v141 offset:5088
	ds_write_b16_d16_hi v178, v141 offset:5360
	ds_write_b16 v178, v142 offset:6720
	ds_write_b16_d16_hi v178, v142 offset:6992
	ds_write_b16 v178, v143 offset:7264
	ds_write_b16_d16_hi v178, v143 offset:7536
	s_waitcnt lgkmcnt(0)
	ds_read_b128 v[80:83], v174 offset:0
	ds_read_b128 v[84:87], v174 offset:1088
	ds_read_b128 v[88:91], v174 offset:2176
	ds_read_b128 v[92:95], v174 offset:3264
	ds_read_b128 v[96:99], v174 offset:4352
	ds_read_b128 v[100:103], v174 offset:5440
	ds_read_b128 v[104:107], v174 offset:6528
	ds_read_b128 v[108:111], v174 offset:7616
	s_waitcnt lgkmcnt(7)
	global_store_dwordx4 v[144:145], v[80:83], off
	v_lshl_add_u64 v[144:145], v[144:145], 0, s[26:27]
	s_waitcnt lgkmcnt(6)
	global_store_dwordx4 v[144:145], v[84:87], off
	v_lshl_add_u64 v[144:145], v[144:145], 0, s[26:27]
	s_waitcnt lgkmcnt(5)
	global_store_dwordx4 v[144:145], v[88:91], off
	v_lshl_add_u64 v[144:145], v[144:145], 0, s[26:27]
	s_waitcnt lgkmcnt(4)
	global_store_dwordx4 v[144:145], v[92:95], off
	v_lshl_add_u64 v[144:145], v[144:145], 0, s[26:27]
	s_waitcnt lgkmcnt(3)
	global_store_dwordx4 v[144:145], v[96:99], off
	v_lshl_add_u64 v[144:145], v[144:145], 0, s[26:27]
	s_waitcnt lgkmcnt(2)
	global_store_dwordx4 v[144:145], v[100:103], off
	v_lshl_add_u64 v[144:145], v[144:145], 0, s[26:27]
	s_waitcnt lgkmcnt(1)
	global_store_dwordx4 v[144:145], v[104:107], off
	v_lshl_add_u64 v[144:145], v[144:145], 0, s[26:27]
	s_waitcnt lgkmcnt(0)
	global_store_dwordx4 v[144:145], v[108:111], off
	s_add_u32 s21, s21, 1
	s_cmp_lt_u32 s21, 2
	s_cbranch_scc1 .Ldsa_half
	s_add_u32 s3, s3, s2
	s_branch .Ldsa_unit
